# GEMM3 (out-projection) epilogue rewritten by hand: x loads pipelined 3 row-groups deep instead of 32 serialized load+wait
# speedup vs baseline: 1.0194x; 1.0106x over previous
.LBB0_869:
	s_cmp_eq_u32 s88, 0x100
	s_cbranch_scc1 .Lepi3_fast
	s_lshr_b32 s5, s8, 4
	s_mul_i32 s38, s5, 0x1800
	s_ashr_i32 s39, s38, 31
	s_lshl_b64 s[38:39], s[38:39], 2
	s_add_u32 s5, s86, s38
	s_addc_u32 s17, s87, s39
	s_add_u32 s38, s5, 0x2000
	v_lshl_or_b32 v202, s4, 8, v213
	s_addc_u32 s39, s17, 0
	s_add_u32 s44, s5, 0x4000
	v_ashrrev_i32_e32 v203, 31, v202
	s_addc_u32 s45, s17, 0
	v_lshlrev_b64 v[4:5], 2, v[202:203]
	v_lshl_add_u64 v[34:35], s[38:39], 0, v[4:5]
	v_lshl_add_u64 v[150:151], s[72:73], 0, v[4:5]
	v_lshl_add_u64 v[4:5], s[44:45], 0, v[4:5]
	global_load_dwordx4 v[62:65], v[34:35], off
	global_load_dwordx4 v[182:185], v[4:5], off
	v_or_b32_e32 v4, 16, v202
	v_ashrrev_i32_e32 v5, 31, v4
	v_lshlrev_b64 v[4:5], 2, v[4:5]
	v_lshl_add_u64 v[34:35], s[38:39], 0, v[4:5]
	v_lshl_add_u64 v[4:5], s[44:45], 0, v[4:5]
	global_load_dwordx4 v[178:181], v[150:151], off
	global_load_dwordx4 v[54:57], v[34:35], off
	global_load_dwordx4 v[170:173], v[150:151], off offset:64
	global_load_dwordx4 v[174:177], v[4:5], off
	v_or_b32_e32 v4, 0x80, v202
	v_ashrrev_i32_e32 v5, 31, v4
	v_lshlrev_b64 v[4:5], 2, v[4:5]
	v_lshl_add_u64 v[34:35], s[38:39], 0, v[4:5]
	v_lshl_add_u64 v[4:5], s[44:45], 0, v[4:5]
	global_load_dwordx4 v[46:49], v[34:35], off
	global_load_dwordx4 v[162:165], v[150:151], off offset:512
	global_load_dwordx4 v[166:169], v[4:5], off
	v_or_b32_e32 v4, 0x90, v202
	v_ashrrev_i32_e32 v5, 31, v4
	v_lshlrev_b64 v[4:5], 2, v[4:5]
	v_lshl_add_u32 v204, s8, 8, v1
	v_lshl_add_u64 v[34:35], s[38:39], 0, v[4:5]
	v_lshl_add_u64 v[4:5], s[44:45], 0, v[4:5]
	v_ashrrev_i32_e32 v205, 31, v204
	global_load_dwordx4 v[34:37], v[34:35], off
	s_nop 0
	global_load_dwordx4 v[154:157], v[150:151], off offset:576
	global_load_dwordx4 v[158:161], v[4:5], off
	v_lshlrev_b64 v[4:5], 10, v[204:205]
	v_lshl_add_u64 v[210:211], v[4:5], 0, v[202:203]
	v_lshl_add_u64 v[208:209], v[210:211], 2, s[48:49]
	global_load_dwordx4 v[150:153], v[208:209], off
	s_mov_b64 s[44:45], -1
	s_and_b64 vcc, exec, s[6:7]
	v_lshl_add_u64 v[206:207], v[210:211], 2, s[84:85]
	s_waitcnt vmcnt(0)
	v_pk_fma_f32 v[152:153], v[40:41], v[64:65], v[152:153]
	v_pk_fma_f32 v[150:151], v[38:39], v[62:63], v[150:151]
	s_cbranch_vccz .LBB0_871
	global_store_dwordx4 v[206:207], v[150:153], off
	s_mov_b64 s[44:45], 0

.Lepi3_fast:
	s_nop 7
	s_nop 7
	v_and_b32_e32 v1, 63, v218
	v_lshrrev_b32_e32 v2, 6, v218
	v_and_b32_e32 v3, 15, v1
	v_lshrrev_b32_e32 v1, 4, v1
	v_lshrrev_b32_e32 v4, 2, v2
	v_and_b32_e32 v2, 3, v2
	v_lshl_add_u32 v3, v4, 6, v3
	s_lshl_b32 s16, s8, 8
	v_add_u32_e32 v3, s16, v3
	v_lshlrev_b32_e32 v4, 5, v2
	v_lshl_add_u32 v4, v1, 2, v4
	s_lshl_b32 s17, s4, 8
	v_add_u32_e32 v4, s17, v4
	s_lshl_b32 s17, s4, 2
	v_lshl_add_u32 v5, v3, 4, v2
	v_add_u32_e32 v5, s17, v5
	v_lshlrev_b32_e32 v248, 2, v5
	v_mov_b32_e32 v249, 0
	s_add_u32 s18, s86, 0x300000
	s_addc_u32 s19, s87, 0
	v_lshl_add_u64 v[248:249], s[18:19], 0, v[248:249]
	v_lshl_add_u32 v214, v3, 10, v4
	v_mov_b32_e32 v215, 0
	v_and_b32_e32 v5, 1, v1
	v_mul_u32_u24_e32 v5, 24, v5
	v_lshl_add_u32 v216, v214, 1, v5
	v_mov_b32_e32 v217, 0
	s_add_u32 s18, s86, 0xa800000
	s_addc_u32 s19, s87, 0
	v_lshl_add_u64 v[246:247], s[18:19], 0, v[216:217]
	s_add_u32 s18, s86, 0x2800000
	s_addc_u32 s19, s87, 0
	v_lshl_add_u64 v[216:217], s[18:19], 0, v[216:217]
	v_lshl_add_u64 v[214:215], v[214:215], 2, s[48:49]
	v_lshlrev_b32_e32 v4, 2, v4
	v_mov_b32_e32 v5, 0
	s_lshr_b32 s16, s8, 4
	s_mul_i32 s16, s16, 0x6000
	s_add_u32 s22, s86, s16
	s_addc_u32 s23, s87, 0
	s_add_u32 s24, s22, 0x2000
	s_addc_u32 s25, s23, 0
	s_add_u32 s22, s22, 0x4000
	s_addc_u32 s23, s23, 0
	v_lshl_add_u64 v[2:3], s[24:25], 0, v[4:5]
	global_load_dwordx4 v[150:153], v[2:3], off
	global_load_dwordx4 v[154:157], v[2:3], off offset:64
	global_load_dwordx4 v[158:161], v[2:3], off offset:512
	global_load_dwordx4 v[162:165], v[2:3], off offset:576
	v_lshl_add_u64 v[2:3], s[72:73], 0, v[4:5]
	global_load_dwordx4 v[166:169], v[2:3], off
	global_load_dwordx4 v[170:173], v[2:3], off offset:64
	global_load_dwordx4 v[174:177], v[2:3], off offset:512
	global_load_dwordx4 v[178:181], v[2:3], off offset:576
	v_lshl_add_u64 v[2:3], s[22:23], 0, v[4:5]
	global_load_dwordx4 v[34:37], v[2:3], off
	global_load_dwordx4 v[46:49], v[2:3], off offset:64
	global_load_dwordx4 v[54:57], v[2:3], off offset:512
	global_load_dwordx4 v[62:65], v[2:3], off offset:576
	s_mov_b64 s[28:29], 0x10000
	s_mov_b64 s[30:31], 0x50000
	s_mov_b64 s[26:27], 0x8000
	s_mov_b64 s[34:35], 0x28000
	s_mov_b64 s[18:19], 0x400
	s_mov_b64 s[16:17], 0x1400
	global_load_dwordx4 v[182:185], v[214:215], off
	global_load_dwordx4 v[186:189], v[214:215], off offset:64
	global_load_dwordx4 v[190:193], v[214:215], off offset:512
	global_load_dwordx4 v[194:197], v[214:215], off offset:576
	v_lshl_add_u64 v[214:215], v[214:215], 0, s[28:29]
	global_load_dwordx4 v[198:201], v[214:215], off
	global_load_dwordx4 v[202:205], v[214:215], off offset:64
	global_load_dwordx4 v[206:209], v[214:215], off offset:512
	global_load_dwordx4 v[210:213], v[214:215], off offset:576
	v_lshl_add_u64 v[214:215], v[214:215], 0, s[28:29]
	global_load_dwordx4 v[220:223], v[214:215], off
	global_load_dwordx4 v[224:227], v[214:215], off offset:64
	global_load_dwordx4 v[228:231], v[214:215], off offset:512
	global_load_dwordx4 v[232:235], v[214:215], off offset:576
	v_lshl_add_u64 v[214:215], v[214:215], 0, s[28:29]
	s_waitcnt vmcnt(12)
	v_pk_add_f32 v[34:35], v[34:35], 1.0 op_sel_hi:[1,0]
	v_pk_add_f32 v[36:37], v[36:37], 1.0 op_sel_hi:[1,0]
	v_pk_add_f32 v[46:47], v[46:47], 1.0 op_sel_hi:[1,0]
	v_pk_add_f32 v[48:49], v[48:49], 1.0 op_sel_hi:[1,0]
	v_pk_add_f32 v[54:55], v[54:55], 1.0 op_sel_hi:[1,0]
	v_pk_add_f32 v[56:57], v[56:57], 1.0 op_sel_hi:[1,0]
	v_pk_add_f32 v[62:63], v[62:63], 1.0 op_sel_hi:[1,0]
	v_pk_add_f32 v[64:65], v[64:65], 1.0 op_sel_hi:[1,0]
	v_pk_mul_f32 v[166:167], v[166:167], v[34:35]
	v_pk_mul_f32 v[168:169], v[168:169], v[36:37]
	v_pk_mul_f32 v[170:171], v[170:171], v[46:47]
	v_pk_mul_f32 v[172:173], v[172:173], v[48:49]
	v_pk_mul_f32 v[174:175], v[174:175], v[54:55]
	v_pk_mul_f32 v[176:177], v[176:177], v[56:57]
	v_pk_mul_f32 v[178:179], v[178:179], v[62:63]
	v_pk_mul_f32 v[180:181], v[180:181], v[64:65]
	s_waitcnt vmcnt(8)
	v_mov_b32_e32 v244, 0
	v_pk_fma_f32 v[182:183], v[38:39], v[150:151], v[182:183]
	v_pk_fma_f32 v[184:185], v[40:41], v[152:153], v[184:185]
	v_pk_mul_f32 v[54:55], v[182:183], v[182:183]
	v_pk_mul_f32 v[56:57], v[182:183], v[166:167]
	v_pk_mul_f32 v[62:63], v[184:185], v[168:169]
	v_pk_fma_f32 v[54:55], v[184:185], v[184:185], v[54:55]
	v_cvt_pk_bf16_f32 v236, v182, v183
	v_cvt_pk_bf16_f32 v237, v184, v185
	v_cvt_pk_bf16_f32 v240, v56, v57
	v_cvt_pk_bf16_f32 v241, v62, v63
	v_add_f32_e32 v54, v54, v55
	v_add_f32_e32 v244, v244, v54
	v_pk_fma_f32 v[186:187], v[146:147], v[154:155], v[186:187]
	v_pk_fma_f32 v[188:189], v[148:149], v[156:157], v[188:189]
	v_pk_mul_f32 v[54:55], v[186:187], v[186:187]
	v_pk_mul_f32 v[56:57], v[186:187], v[170:171]
	v_pk_mul_f32 v[62:63], v[188:189], v[172:173]
	v_pk_fma_f32 v[54:55], v[188:189], v[188:189], v[54:55]
	v_cvt_pk_bf16_f32 v238, v186, v187
	v_cvt_pk_bf16_f32 v239, v188, v189
	v_cvt_pk_bf16_f32 v242, v56, v57
	v_cvt_pk_bf16_f32 v243, v62, v63
	v_add_f32_e32 v54, v54, v55
	v_add_f32_e32 v244, v244, v54
	v_permlane16_swap_b32_e32 v236, v238
	v_permlane16_swap_b32_e32 v237, v239
	v_permlane16_swap_b32_e32 v240, v242
	v_permlane16_swap_b32_e32 v241, v243
	global_store_dwordx4 v[246:247], v[236:239], off
	global_store_dwordx4 v[216:217], v[240:243], off
	v_pk_fma_f32 v[190:191], v[142:143], v[158:159], v[190:191]
	v_pk_fma_f32 v[192:193], v[144:145], v[160:161], v[192:193]
	v_pk_mul_f32 v[54:55], v[190:191], v[190:191]
	v_pk_mul_f32 v[56:57], v[190:191], v[174:175]
	v_pk_mul_f32 v[62:63], v[192:193], v[176:177]
	v_pk_fma_f32 v[54:55], v[192:193], v[192:193], v[54:55]
	v_cvt_pk_bf16_f32 v34, v190, v191
	v_cvt_pk_bf16_f32 v35, v192, v193
	v_cvt_pk_bf16_f32 v46, v56, v57
	v_cvt_pk_bf16_f32 v47, v62, v63
	v_add_f32_e32 v54, v54, v55
	v_add_f32_e32 v244, v244, v54
	v_pk_fma_f32 v[194:195], v[138:139], v[162:163], v[194:195]
	v_pk_fma_f32 v[196:197], v[140:141], v[164:165], v[196:197]
	v_pk_mul_f32 v[54:55], v[194:195], v[194:195]
	v_pk_mul_f32 v[56:57], v[194:195], v[178:179]
	v_pk_mul_f32 v[62:63], v[196:197], v[180:181]
	v_pk_fma_f32 v[54:55], v[196:197], v[196:197], v[54:55]
	v_cvt_pk_bf16_f32 v36, v194, v195
	v_cvt_pk_bf16_f32 v37, v196, v197
	v_cvt_pk_bf16_f32 v48, v56, v57
	v_cvt_pk_bf16_f32 v49, v62, v63
	v_add_f32_e32 v54, v54, v55
	v_add_f32_e32 v244, v244, v54
	v_permlane16_swap_b32_e32 v34, v36
	v_permlane16_swap_b32_e32 v35, v37
	v_permlane16_swap_b32_e32 v46, v48
	v_permlane16_swap_b32_e32 v47, v49
	global_store_dwordx4 v[246:247], v[34:37], off offset:256
	global_store_dwordx4 v[216:217], v[46:49], off offset:256
	v_mov_b32_e32 v54, v244
	v_mov_b32_e32 v55, v244
	s_nop 1
	v_permlane32_swap_b32_e32 v54, v55
	v_add_f32_e32 v244, v244, v55
	v_mov_b32_e32 v54, v244
	v_mov_b32_e32 v55, v244
	s_nop 1
	v_permlane16_swap_b32_e32 v54, v55
	v_add_f32_e32 v244, v244, v55
	s_mov_b64 exec, 0xffff
	global_store_dword v[248:249], v244, off
	s_mov_b64 exec, -1
	v_lshl_add_u64 v[246:247], v[246:247], 0, s[26:27]
	v_lshl_add_u64 v[216:217], v[216:217], 0, s[26:27]
	v_lshl_add_u64 v[248:249], v[248:249], 0, s[18:19]
	global_load_dwordx4 v[182:185], v[214:215], off
	global_load_dwordx4 v[186:189], v[214:215], off offset:64
	global_load_dwordx4 v[190:193], v[214:215], off offset:512
	global_load_dwordx4 v[194:197], v[214:215], off offset:576
	v_lshl_add_u64 v[214:215], v[214:215], 0, s[30:31]
	s_waitcnt vmcnt(12)
	v_mov_b32_e32 v244, 0
	v_pk_fma_f32 v[198:199], v[134:135], v[150:151], v[198:199]
	v_pk_fma_f32 v[200:201], v[136:137], v[152:153], v[200:201]
	v_pk_mul_f32 v[54:55], v[198:199], v[198:199]
	v_pk_mul_f32 v[56:57], v[198:199], v[166:167]
	v_pk_mul_f32 v[62:63], v[200:201], v[168:169]
	v_pk_fma_f32 v[54:55], v[200:201], v[200:201], v[54:55]
	v_cvt_pk_bf16_f32 v236, v198, v199
	v_cvt_pk_bf16_f32 v237, v200, v201
	v_cvt_pk_bf16_f32 v240, v56, v57
	v_cvt_pk_bf16_f32 v241, v62, v63
	v_add_f32_e32 v54, v54, v55
	v_add_f32_e32 v244, v244, v54
	v_pk_fma_f32 v[202:203], v[130:131], v[154:155], v[202:203]
	v_pk_fma_f32 v[204:205], v[132:133], v[156:157], v[204:205]
	v_pk_mul_f32 v[54:55], v[202:203], v[202:203]
	v_pk_mul_f32 v[56:57], v[202:203], v[170:171]
	v_pk_mul_f32 v[62:63], v[204:205], v[172:173]
	v_pk_fma_f32 v[54:55], v[204:205], v[204:205], v[54:55]
	v_cvt_pk_bf16_f32 v238, v202, v203
	v_cvt_pk_bf16_f32 v239, v204, v205
	v_cvt_pk_bf16_f32 v242, v56, v57
	v_cvt_pk_bf16_f32 v243, v62, v63
	v_add_f32_e32 v54, v54, v55
	v_add_f32_e32 v244, v244, v54
	v_permlane16_swap_b32_e32 v236, v238
	v_permlane16_swap_b32_e32 v237, v239
	v_permlane16_swap_b32_e32 v240, v242
	v_permlane16_swap_b32_e32 v241, v243
	global_store_dwordx4 v[246:247], v[236:239], off
	global_store_dwordx4 v[216:217], v[240:243], off
	v_pk_fma_f32 v[206:207], v[126:127], v[158:159], v[206:207]
	v_pk_fma_f32 v[208:209], v[128:129], v[160:161], v[208:209]
	v_pk_mul_f32 v[54:55], v[206:207], v[206:207]
	v_pk_mul_f32 v[56:57], v[206:207], v[174:175]
	v_pk_mul_f32 v[62:63], v[208:209], v[176:177]
	v_pk_fma_f32 v[54:55], v[208:209], v[208:209], v[54:55]
	v_cvt_pk_bf16_f32 v34, v206, v207
	v_cvt_pk_bf16_f32 v35, v208, v209
	v_cvt_pk_bf16_f32 v46, v56, v57
	v_cvt_pk_bf16_f32 v47, v62, v63
	v_add_f32_e32 v54, v54, v55
	v_add_f32_e32 v244, v244, v54
	v_pk_fma_f32 v[210:211], v[122:123], v[162:163], v[210:211]
	v_pk_fma_f32 v[212:213], v[124:125], v[164:165], v[212:213]
	v_pk_mul_f32 v[54:55], v[210:211], v[210:211]
	v_pk_mul_f32 v[56:57], v[210:211], v[178:179]
	v_pk_mul_f32 v[62:63], v[212:213], v[180:181]
	v_pk_fma_f32 v[54:55], v[212:213], v[212:213], v[54:55]
	v_cvt_pk_bf16_f32 v36, v210, v211
	v_cvt_pk_bf16_f32 v37, v212, v213
	v_cvt_pk_bf16_f32 v48, v56, v57
	v_cvt_pk_bf16_f32 v49, v62, v63
	v_add_f32_e32 v54, v54, v55
	v_add_f32_e32 v244, v244, v54
	v_permlane16_swap_b32_e32 v34, v36
	v_permlane16_swap_b32_e32 v35, v37
	v_permlane16_swap_b32_e32 v46, v48
	v_permlane16_swap_b32_e32 v47, v49
	global_store_dwordx4 v[246:247], v[34:37], off offset:256
	global_store_dwordx4 v[216:217], v[46:49], off offset:256
	v_mov_b32_e32 v54, v244
	v_mov_b32_e32 v55, v244
	s_nop 1
	v_permlane32_swap_b32_e32 v54, v55
	v_add_f32_e32 v244, v244, v55
	v_mov_b32_e32 v54, v244
	v_mov_b32_e32 v55, v244
	s_nop 1
	v_permlane16_swap_b32_e32 v54, v55
	v_add_f32_e32 v244, v244, v55
	s_mov_b64 exec, 0xffff
	global_store_dword v[248:249], v244, off
	s_mov_b64 exec, -1
	v_lshl_add_u64 v[246:247], v[246:247], 0, s[26:27]
	v_lshl_add_u64 v[216:217], v[216:217], 0, s[26:27]
	v_lshl_add_u64 v[248:249], v[248:249], 0, s[18:19]
	global_load_dwordx4 v[198:201], v[214:215], off
	global_load_dwordx4 v[202:205], v[214:215], off offset:64
	global_load_dwordx4 v[206:209], v[214:215], off offset:512
	global_load_dwordx4 v[210:213], v[214:215], off offset:576
	v_lshl_add_u64 v[214:215], v[214:215], 0, s[28:29]
	s_waitcnt vmcnt(16)
	v_mov_b32_e32 v244, 0
	v_pk_fma_f32 v[220:221], v[118:119], v[150:151], v[220:221]
	v_pk_fma_f32 v[222:223], v[120:121], v[152:153], v[222:223]
	v_pk_mul_f32 v[54:55], v[220:221], v[220:221]
	v_pk_mul_f32 v[56:57], v[220:221], v[166:167]
	v_pk_mul_f32 v[62:63], v[222:223], v[168:169]
	v_pk_fma_f32 v[54:55], v[222:223], v[222:223], v[54:55]
	v_cvt_pk_bf16_f32 v236, v220, v221
	v_cvt_pk_bf16_f32 v237, v222, v223
	v_cvt_pk_bf16_f32 v240, v56, v57
	v_cvt_pk_bf16_f32 v241, v62, v63
	v_add_f32_e32 v54, v54, v55
	v_add_f32_e32 v244, v244, v54
	v_pk_fma_f32 v[224:225], v[114:115], v[154:155], v[224:225]
	v_pk_fma_f32 v[226:227], v[116:117], v[156:157], v[226:227]
	v_pk_mul_f32 v[54:55], v[224:225], v[224:225]
	v_pk_mul_f32 v[56:57], v[224:225], v[170:171]
	v_pk_mul_f32 v[62:63], v[226:227], v[172:173]
	v_pk_fma_f32 v[54:55], v[226:227], v[226:227], v[54:55]
	v_cvt_pk_bf16_f32 v238, v224, v225
	v_cvt_pk_bf16_f32 v239, v226, v227
	v_cvt_pk_bf16_f32 v242, v56, v57
	v_cvt_pk_bf16_f32 v243, v62, v63
	v_add_f32_e32 v54, v54, v55
	v_add_f32_e32 v244, v244, v54
	v_permlane16_swap_b32_e32 v236, v238
	v_permlane16_swap_b32_e32 v237, v239
	v_permlane16_swap_b32_e32 v240, v242
	v_permlane16_swap_b32_e32 v241, v243
	global_store_dwordx4 v[246:247], v[236:239], off
	global_store_dwordx4 v[216:217], v[240:243], off
	v_pk_fma_f32 v[228:229], v[110:111], v[158:159], v[228:229]
	v_pk_fma_f32 v[230:231], v[112:113], v[160:161], v[230:231]
	v_pk_mul_f32 v[54:55], v[228:229], v[228:229]
	v_pk_mul_f32 v[56:57], v[228:229], v[174:175]
	v_pk_mul_f32 v[62:63], v[230:231], v[176:177]
	v_pk_fma_f32 v[54:55], v[230:231], v[230:231], v[54:55]
	v_cvt_pk_bf16_f32 v34, v228, v229
	v_cvt_pk_bf16_f32 v35, v230, v231
	v_cvt_pk_bf16_f32 v46, v56, v57
	v_cvt_pk_bf16_f32 v47, v62, v63
	v_add_f32_e32 v54, v54, v55
	v_add_f32_e32 v244, v244, v54
	v_pk_fma_f32 v[232:233], v[106:107], v[162:163], v[232:233]
	v_pk_fma_f32 v[234:235], v[108:109], v[164:165], v[234:235]
	v_pk_mul_f32 v[54:55], v[232:233], v[232:233]
	v_pk_mul_f32 v[56:57], v[232:233], v[178:179]
	v_pk_mul_f32 v[62:63], v[234:235], v[180:181]
	v_pk_fma_f32 v[54:55], v[234:235], v[234:235], v[54:55]
	v_cvt_pk_bf16_f32 v36, v232, v233
	v_cvt_pk_bf16_f32 v37, v234, v235
	v_cvt_pk_bf16_f32 v48, v56, v57
	v_cvt_pk_bf16_f32 v49, v62, v63
	v_add_f32_e32 v54, v54, v55
	v_add_f32_e32 v244, v244, v54
	v_permlane16_swap_b32_e32 v34, v36
	v_permlane16_swap_b32_e32 v35, v37
	v_permlane16_swap_b32_e32 v46, v48
	v_permlane16_swap_b32_e32 v47, v49
	global_store_dwordx4 v[246:247], v[34:37], off offset:256
	global_store_dwordx4 v[216:217], v[46:49], off offset:256
	v_mov_b32_e32 v54, v244
	v_mov_b32_e32 v55, v244
	s_nop 1
	v_permlane32_swap_b32_e32 v54, v55
	v_add_f32_e32 v244, v244, v55
	v_mov_b32_e32 v54, v244
	v_mov_b32_e32 v55, v244
	s_nop 1
	v_permlane16_swap_b32_e32 v54, v55
	v_add_f32_e32 v244, v244, v55
	s_mov_b64 exec, 0xffff
	global_store_dword v[248:249], v244, off
	s_mov_b64 exec, -1
	v_lshl_add_u64 v[246:247], v[246:247], 0, s[26:27]
	v_lshl_add_u64 v[216:217], v[216:217], 0, s[26:27]
	v_lshl_add_u64 v[248:249], v[248:249], 0, s[18:19]
	global_load_dwordx4 v[220:223], v[214:215], off
	global_load_dwordx4 v[224:227], v[214:215], off offset:64
	global_load_dwordx4 v[228:231], v[214:215], off offset:512
	global_load_dwordx4 v[232:235], v[214:215], off offset:576
	v_lshl_add_u64 v[214:215], v[214:215], 0, s[28:29]
	s_waitcnt vmcnt(16)
	v_mov_b32_e32 v244, 0
	v_pk_fma_f32 v[182:183], v[102:103], v[150:151], v[182:183]
	v_pk_fma_f32 v[184:185], v[104:105], v[152:153], v[184:185]
	v_pk_mul_f32 v[54:55], v[182:183], v[182:183]
	v_pk_mul_f32 v[56:57], v[182:183], v[166:167]
	v_pk_mul_f32 v[62:63], v[184:185], v[168:169]
	v_pk_fma_f32 v[54:55], v[184:185], v[184:185], v[54:55]
	v_cvt_pk_bf16_f32 v236, v182, v183
	v_cvt_pk_bf16_f32 v237, v184, v185
	v_cvt_pk_bf16_f32 v240, v56, v57
	v_cvt_pk_bf16_f32 v241, v62, v63
	v_add_f32_e32 v54, v54, v55
	v_add_f32_e32 v244, v244, v54
	v_pk_fma_f32 v[186:187], v[98:99], v[154:155], v[186:187]
	v_pk_fma_f32 v[188:189], v[100:101], v[156:157], v[188:189]
	v_pk_mul_f32 v[54:55], v[186:187], v[186:187]
	v_pk_mul_f32 v[56:57], v[186:187], v[170:171]
	v_pk_mul_f32 v[62:63], v[188:189], v[172:173]
	v_pk_fma_f32 v[54:55], v[188:189], v[188:189], v[54:55]
	v_cvt_pk_bf16_f32 v238, v186, v187
	v_cvt_pk_bf16_f32 v239, v188, v189
	v_cvt_pk_bf16_f32 v242, v56, v57
	v_cvt_pk_bf16_f32 v243, v62, v63
	v_add_f32_e32 v54, v54, v55
	v_add_f32_e32 v244, v244, v54
	v_permlane16_swap_b32_e32 v236, v238
	v_permlane16_swap_b32_e32 v237, v239
	v_permlane16_swap_b32_e32 v240, v242
	v_permlane16_swap_b32_e32 v241, v243
	global_store_dwordx4 v[246:247], v[236:239], off
	global_store_dwordx4 v[216:217], v[240:243], off
	v_pk_fma_f32 v[190:191], v[94:95], v[158:159], v[190:191]
	v_pk_fma_f32 v[192:193], v[96:97], v[160:161], v[192:193]
	v_pk_mul_f32 v[54:55], v[190:191], v[190:191]
	v_pk_mul_f32 v[56:57], v[190:191], v[174:175]
	v_pk_mul_f32 v[62:63], v[192:193], v[176:177]
	v_pk_fma_f32 v[54:55], v[192:193], v[192:193], v[54:55]
	v_cvt_pk_bf16_f32 v34, v190, v191
	v_cvt_pk_bf16_f32 v35, v192, v193
	v_cvt_pk_bf16_f32 v46, v56, v57
	v_cvt_pk_bf16_f32 v47, v62, v63
	v_add_f32_e32 v54, v54, v55
	v_add_f32_e32 v244, v244, v54
	v_pk_fma_f32 v[194:195], v[90:91], v[162:163], v[194:195]
	v_pk_fma_f32 v[196:197], v[92:93], v[164:165], v[196:197]
	v_pk_mul_f32 v[54:55], v[194:195], v[194:195]
	v_pk_mul_f32 v[56:57], v[194:195], v[178:179]
	v_pk_mul_f32 v[62:63], v[196:197], v[180:181]
	v_pk_fma_f32 v[54:55], v[196:197], v[196:197], v[54:55]
	v_cvt_pk_bf16_f32 v36, v194, v195
	v_cvt_pk_bf16_f32 v37, v196, v197
	v_cvt_pk_bf16_f32 v48, v56, v57
	v_cvt_pk_bf16_f32 v49, v62, v63
	v_add_f32_e32 v54, v54, v55
	v_add_f32_e32 v244, v244, v54
	v_permlane16_swap_b32_e32 v34, v36
	v_permlane16_swap_b32_e32 v35, v37
	v_permlane16_swap_b32_e32 v46, v48
	v_permlane16_swap_b32_e32 v47, v49
	global_store_dwordx4 v[246:247], v[34:37], off offset:256
	global_store_dwordx4 v[216:217], v[46:49], off offset:256
	v_mov_b32_e32 v54, v244
	v_mov_b32_e32 v55, v244
	s_nop 1
	v_permlane32_swap_b32_e32 v54, v55
	v_add_f32_e32 v244, v244, v55
	v_mov_b32_e32 v54, v244
	v_mov_b32_e32 v55, v244
	s_nop 1
	v_permlane16_swap_b32_e32 v54, v55
	v_add_f32_e32 v244, v244, v55
	s_mov_b64 exec, 0xffff
	global_store_dword v[248:249], v244, off
	s_mov_b64 exec, -1
	v_lshl_add_u64 v[246:247], v[246:247], 0, s[34:35]
	v_lshl_add_u64 v[216:217], v[216:217], 0, s[34:35]
	v_lshl_add_u64 v[248:249], v[248:249], 0, s[16:17]
	global_load_dwordx4 v[182:185], v[214:215], off
	global_load_dwordx4 v[186:189], v[214:215], off offset:64
	global_load_dwordx4 v[190:193], v[214:215], off offset:512
	global_load_dwordx4 v[194:197], v[214:215], off offset:576
	v_lshl_add_u64 v[214:215], v[214:215], 0, s[28:29]
	s_waitcnt vmcnt(16)
	v_mov_b32_e32 v244, 0
	v_pk_fma_f32 v[198:199], v[86:87], v[150:151], v[198:199]
	v_pk_fma_f32 v[200:201], v[88:89], v[152:153], v[200:201]
	v_pk_mul_f32 v[54:55], v[198:199], v[198:199]
	v_pk_mul_f32 v[56:57], v[198:199], v[166:167]
	v_pk_mul_f32 v[62:63], v[200:201], v[168:169]
	v_pk_fma_f32 v[54:55], v[200:201], v[200:201], v[54:55]
	v_cvt_pk_bf16_f32 v236, v198, v199
	v_cvt_pk_bf16_f32 v237, v200, v201
	v_cvt_pk_bf16_f32 v240, v56, v57
	v_cvt_pk_bf16_f32 v241, v62, v63
	v_add_f32_e32 v54, v54, v55
	v_add_f32_e32 v244, v244, v54
	v_pk_fma_f32 v[202:203], v[82:83], v[154:155], v[202:203]
	v_pk_fma_f32 v[204:205], v[84:85], v[156:157], v[204:205]
	v_pk_mul_f32 v[54:55], v[202:203], v[202:203]
	v_pk_mul_f32 v[56:57], v[202:203], v[170:171]
	v_pk_mul_f32 v[62:63], v[204:205], v[172:173]
	v_pk_fma_f32 v[54:55], v[204:205], v[204:205], v[54:55]
	v_cvt_pk_bf16_f32 v238, v202, v203
	v_cvt_pk_bf16_f32 v239, v204, v205
	v_cvt_pk_bf16_f32 v242, v56, v57
	v_cvt_pk_bf16_f32 v243, v62, v63
	v_add_f32_e32 v54, v54, v55
	v_add_f32_e32 v244, v244, v54
	v_permlane16_swap_b32_e32 v236, v238
	v_permlane16_swap_b32_e32 v237, v239
	v_permlane16_swap_b32_e32 v240, v242
	v_permlane16_swap_b32_e32 v241, v243
	global_store_dwordx4 v[246:247], v[236:239], off
	global_store_dwordx4 v[216:217], v[240:243], off
	v_pk_fma_f32 v[206:207], v[78:79], v[158:159], v[206:207]
	v_pk_fma_f32 v[208:209], v[80:81], v[160:161], v[208:209]
	v_pk_mul_f32 v[54:55], v[206:207], v[206:207]
	v_pk_mul_f32 v[56:57], v[206:207], v[174:175]
	v_pk_mul_f32 v[62:63], v[208:209], v[176:177]
	v_pk_fma_f32 v[54:55], v[208:209], v[208:209], v[54:55]
	v_cvt_pk_bf16_f32 v34, v206, v207
	v_cvt_pk_bf16_f32 v35, v208, v209
	v_cvt_pk_bf16_f32 v46, v56, v57
	v_cvt_pk_bf16_f32 v47, v62, v63
	v_add_f32_e32 v54, v54, v55
	v_add_f32_e32 v244, v244, v54
	v_pk_fma_f32 v[210:211], v[74:75], v[162:163], v[210:211]
	v_pk_fma_f32 v[212:213], v[76:77], v[164:165], v[212:213]
	v_pk_mul_f32 v[54:55], v[210:211], v[210:211]
	v_pk_mul_f32 v[56:57], v[210:211], v[178:179]
	v_pk_mul_f32 v[62:63], v[212:213], v[180:181]
	v_pk_fma_f32 v[54:55], v[212:213], v[212:213], v[54:55]
	v_cvt_pk_bf16_f32 v36, v210, v211
	v_cvt_pk_bf16_f32 v37, v212, v213
	v_cvt_pk_bf16_f32 v48, v56, v57
	v_cvt_pk_bf16_f32 v49, v62, v63
	v_add_f32_e32 v54, v54, v55
	v_add_f32_e32 v244, v244, v54
	v_permlane16_swap_b32_e32 v34, v36
	v_permlane16_swap_b32_e32 v35, v37
	v_permlane16_swap_b32_e32 v46, v48
	v_permlane16_swap_b32_e32 v47, v49
	global_store_dwordx4 v[246:247], v[34:37], off offset:256
	global_store_dwordx4 v[216:217], v[46:49], off offset:256
	v_mov_b32_e32 v54, v244
	v_mov_b32_e32 v55, v244
	s_nop 1
	v_permlane32_swap_b32_e32 v54, v55
	v_add_f32_e32 v244, v244, v55
	v_mov_b32_e32 v54, v244
	v_mov_b32_e32 v55, v244
	s_nop 1
	v_permlane16_swap_b32_e32 v54, v55
	v_add_f32_e32 v244, v244, v55
	s_mov_b64 exec, 0xffff
	global_store_dword v[248:249], v244, off
	s_mov_b64 exec, -1
	v_lshl_add_u64 v[246:247], v[246:247], 0, s[26:27]
	v_lshl_add_u64 v[216:217], v[216:217], 0, s[26:27]
	v_lshl_add_u64 v[248:249], v[248:249], 0, s[18:19]
	global_load_dwordx4 v[198:201], v[214:215], off
	global_load_dwordx4 v[202:205], v[214:215], off offset:64
	global_load_dwordx4 v[206:209], v[214:215], off offset:512
	global_load_dwordx4 v[210:213], v[214:215], off offset:576
	s_waitcnt vmcnt(16)
	v_mov_b32_e32 v244, 0
	v_pk_fma_f32 v[220:221], v[70:71], v[150:151], v[220:221]
	v_pk_fma_f32 v[222:223], v[72:73], v[152:153], v[222:223]
	v_pk_mul_f32 v[54:55], v[220:221], v[220:221]
	v_pk_mul_f32 v[56:57], v[220:221], v[166:167]
	v_pk_mul_f32 v[62:63], v[222:223], v[168:169]
	v_pk_fma_f32 v[54:55], v[222:223], v[222:223], v[54:55]
	v_cvt_pk_bf16_f32 v236, v220, v221
	v_cvt_pk_bf16_f32 v237, v222, v223
	v_cvt_pk_bf16_f32 v240, v56, v57
	v_cvt_pk_bf16_f32 v241, v62, v63
	v_add_f32_e32 v54, v54, v55
	v_add_f32_e32 v244, v244, v54
	v_pk_fma_f32 v[224:225], v[66:67], v[154:155], v[224:225]
	v_pk_fma_f32 v[226:227], v[68:69], v[156:157], v[226:227]
	v_pk_mul_f32 v[54:55], v[224:225], v[224:225]
	v_pk_mul_f32 v[56:57], v[224:225], v[170:171]
	v_pk_mul_f32 v[62:63], v[226:227], v[172:173]
	v_pk_fma_f32 v[54:55], v[226:227], v[226:227], v[54:55]
	v_cvt_pk_bf16_f32 v238, v224, v225
	v_cvt_pk_bf16_f32 v239, v226, v227
	v_cvt_pk_bf16_f32 v242, v56, v57
	v_cvt_pk_bf16_f32 v243, v62, v63
	v_add_f32_e32 v54, v54, v55
	v_add_f32_e32 v244, v244, v54
	v_permlane16_swap_b32_e32 v236, v238
	v_permlane16_swap_b32_e32 v237, v239
	v_permlane16_swap_b32_e32 v240, v242
	v_permlane16_swap_b32_e32 v241, v243
	global_store_dwordx4 v[246:247], v[236:239], off
	global_store_dwordx4 v[216:217], v[240:243], off
	v_pk_fma_f32 v[228:229], v[58:59], v[158:159], v[228:229]
	v_pk_fma_f32 v[230:231], v[60:61], v[160:161], v[230:231]
	v_pk_mul_f32 v[54:55], v[228:229], v[228:229]
	v_pk_mul_f32 v[56:57], v[228:229], v[174:175]
	v_pk_mul_f32 v[62:63], v[230:231], v[176:177]
	v_pk_fma_f32 v[54:55], v[230:231], v[230:231], v[54:55]
	v_cvt_pk_bf16_f32 v34, v228, v229
	v_cvt_pk_bf16_f32 v35, v230, v231
	v_cvt_pk_bf16_f32 v46, v56, v57
	v_cvt_pk_bf16_f32 v47, v62, v63
	v_add_f32_e32 v54, v54, v55
	v_add_f32_e32 v244, v244, v54
	v_pk_fma_f32 v[232:233], v[50:51], v[162:163], v[232:233]
	v_pk_fma_f32 v[234:235], v[52:53], v[164:165], v[234:235]
	v_pk_mul_f32 v[54:55], v[232:233], v[232:233]
	v_pk_mul_f32 v[56:57], v[232:233], v[178:179]
	v_pk_mul_f32 v[62:63], v[234:235], v[180:181]
	v_pk_fma_f32 v[54:55], v[234:235], v[234:235], v[54:55]
	v_cvt_pk_bf16_f32 v36, v232, v233
	v_cvt_pk_bf16_f32 v37, v234, v235
	v_cvt_pk_bf16_f32 v48, v56, v57
	v_cvt_pk_bf16_f32 v49, v62, v63
	v_add_f32_e32 v54, v54, v55
	v_add_f32_e32 v244, v244, v54
	v_permlane16_swap_b32_e32 v34, v36
	v_permlane16_swap_b32_e32 v35, v37
	v_permlane16_swap_b32_e32 v46, v48
	v_permlane16_swap_b32_e32 v47, v49
	global_store_dwordx4 v[246:247], v[34:37], off offset:256
	global_store_dwordx4 v[216:217], v[46:49], off offset:256
	v_mov_b32_e32 v54, v244
	v_mov_b32_e32 v55, v244
	s_nop 1
	v_permlane32_swap_b32_e32 v54, v55
	v_add_f32_e32 v244, v244, v55
	v_mov_b32_e32 v54, v244
	v_mov_b32_e32 v55, v244
	s_nop 1
	v_permlane16_swap_b32_e32 v54, v55
	v_add_f32_e32 v244, v244, v55
	s_mov_b64 exec, 0xffff
	global_store_dword v[248:249], v244, off
	s_mov_b64 exec, -1
	v_lshl_add_u64 v[246:247], v[246:247], 0, s[26:27]
	v_lshl_add_u64 v[216:217], v[216:217], 0, s[26:27]
	v_lshl_add_u64 v[248:249], v[248:249], 0, s[18:19]
	s_waitcnt vmcnt(12)
	v_mov_b32_e32 v244, 0
	v_pk_fma_f32 v[182:183], v[42:43], v[150:151], v[182:183]
	v_pk_fma_f32 v[184:185], v[44:45], v[152:153], v[184:185]
	v_pk_mul_f32 v[54:55], v[182:183], v[182:183]
	v_pk_mul_f32 v[56:57], v[182:183], v[166:167]
	v_pk_mul_f32 v[62:63], v[184:185], v[168:169]
	v_pk_fma_f32 v[54:55], v[184:185], v[184:185], v[54:55]
	v_cvt_pk_bf16_f32 v236, v182, v183
	v_cvt_pk_bf16_f32 v237, v184, v185
	v_cvt_pk_bf16_f32 v240, v56, v57
	v_cvt_pk_bf16_f32 v241, v62, v63
	v_add_f32_e32 v54, v54, v55
	v_add_f32_e32 v244, v244, v54
	v_pk_fma_f32 v[186:187], v[30:31], v[154:155], v[186:187]
	v_pk_fma_f32 v[188:189], v[32:33], v[156:157], v[188:189]
	v_pk_mul_f32 v[54:55], v[186:187], v[186:187]
	v_pk_mul_f32 v[56:57], v[186:187], v[170:171]
	v_pk_mul_f32 v[62:63], v[188:189], v[172:173]
	v_pk_fma_f32 v[54:55], v[188:189], v[188:189], v[54:55]
	v_cvt_pk_bf16_f32 v238, v186, v187
	v_cvt_pk_bf16_f32 v239, v188, v189
	v_cvt_pk_bf16_f32 v242, v56, v57
	v_cvt_pk_bf16_f32 v243, v62, v63
	v_add_f32_e32 v54, v54, v55
	v_add_f32_e32 v244, v244, v54
	v_permlane16_swap_b32_e32 v236, v238
	v_permlane16_swap_b32_e32 v237, v239
	v_permlane16_swap_b32_e32 v240, v242
	v_permlane16_swap_b32_e32 v241, v243
	global_store_dwordx4 v[246:247], v[236:239], off
	global_store_dwordx4 v[216:217], v[240:243], off
	v_pk_fma_f32 v[190:191], v[26:27], v[158:159], v[190:191]
	v_pk_fma_f32 v[192:193], v[28:29], v[160:161], v[192:193]
	v_pk_mul_f32 v[54:55], v[190:191], v[190:191]
	v_pk_mul_f32 v[56:57], v[190:191], v[174:175]
	v_pk_mul_f32 v[62:63], v[192:193], v[176:177]
	v_pk_fma_f32 v[54:55], v[192:193], v[192:193], v[54:55]
	v_cvt_pk_bf16_f32 v34, v190, v191
	v_cvt_pk_bf16_f32 v35, v192, v193
	v_cvt_pk_bf16_f32 v46, v56, v57
	v_cvt_pk_bf16_f32 v47, v62, v63
	v_add_f32_e32 v54, v54, v55
	v_add_f32_e32 v244, v244, v54
	v_pk_fma_f32 v[194:195], v[22:23], v[162:163], v[194:195]
	v_pk_fma_f32 v[196:197], v[24:25], v[164:165], v[196:197]
	v_pk_mul_f32 v[54:55], v[194:195], v[194:195]
	v_pk_mul_f32 v[56:57], v[194:195], v[178:179]
	v_pk_mul_f32 v[62:63], v[196:197], v[180:181]
	v_pk_fma_f32 v[54:55], v[196:197], v[196:197], v[54:55]
	v_cvt_pk_bf16_f32 v36, v194, v195
	v_cvt_pk_bf16_f32 v37, v196, v197
	v_cvt_pk_bf16_f32 v48, v56, v57
	v_cvt_pk_bf16_f32 v49, v62, v63
	v_add_f32_e32 v54, v54, v55
	v_add_f32_e32 v244, v244, v54
	v_permlane16_swap_b32_e32 v34, v36
	v_permlane16_swap_b32_e32 v35, v37
	v_permlane16_swap_b32_e32 v46, v48
	v_permlane16_swap_b32_e32 v47, v49
	global_store_dwordx4 v[246:247], v[34:37], off offset:256
	global_store_dwordx4 v[216:217], v[46:49], off offset:256
	v_mov_b32_e32 v54, v244
	v_mov_b32_e32 v55, v244
	s_nop 1
	v_permlane32_swap_b32_e32 v54, v55
	v_add_f32_e32 v244, v244, v55
	v_mov_b32_e32 v54, v244
	v_mov_b32_e32 v55, v244
	s_nop 1
	v_permlane16_swap_b32_e32 v54, v55
	v_add_f32_e32 v244, v244, v55
	s_mov_b64 exec, 0xffff
	global_store_dword v[248:249], v244, off
	s_mov_b64 exec, -1
	v_lshl_add_u64 v[246:247], v[246:247], 0, s[26:27]
	v_lshl_add_u64 v[216:217], v[216:217], 0, s[26:27]
	v_lshl_add_u64 v[248:249], v[248:249], 0, s[18:19]
	s_waitcnt vmcnt(8)
	v_mov_b32_e32 v244, 0
	v_pk_fma_f32 v[198:199], v[18:19], v[150:151], v[198:199]
	v_pk_fma_f32 v[200:201], v[20:21], v[152:153], v[200:201]
	v_pk_mul_f32 v[54:55], v[198:199], v[198:199]
	v_pk_mul_f32 v[56:57], v[198:199], v[166:167]
	v_pk_mul_f32 v[62:63], v[200:201], v[168:169]
	v_pk_fma_f32 v[54:55], v[200:201], v[200:201], v[54:55]
	v_cvt_pk_bf16_f32 v236, v198, v199
	v_cvt_pk_bf16_f32 v237, v200, v201
	v_cvt_pk_bf16_f32 v240, v56, v57
	v_cvt_pk_bf16_f32 v241, v62, v63
	v_add_f32_e32 v54, v54, v55
	v_add_f32_e32 v244, v244, v54
	v_pk_fma_f32 v[202:203], v[14:15], v[154:155], v[202:203]
	v_pk_fma_f32 v[204:205], v[16:17], v[156:157], v[204:205]
	v_pk_mul_f32 v[54:55], v[202:203], v[202:203]
	v_pk_mul_f32 v[56:57], v[202:203], v[170:171]
	v_pk_mul_f32 v[62:63], v[204:205], v[172:173]
	v_pk_fma_f32 v[54:55], v[204:205], v[204:205], v[54:55]
	v_cvt_pk_bf16_f32 v238, v202, v203
	v_cvt_pk_bf16_f32 v239, v204, v205
	v_cvt_pk_bf16_f32 v242, v56, v57
	v_cvt_pk_bf16_f32 v243, v62, v63
	v_add_f32_e32 v54, v54, v55
	v_add_f32_e32 v244, v244, v54
	v_permlane16_swap_b32_e32 v236, v238
	v_permlane16_swap_b32_e32 v237, v239
	v_permlane16_swap_b32_e32 v240, v242
	v_permlane16_swap_b32_e32 v241, v243
	global_store_dwordx4 v[246:247], v[236:239], off
	global_store_dwordx4 v[216:217], v[240:243], off
	v_pk_fma_f32 v[206:207], v[10:11], v[158:159], v[206:207]
	v_pk_fma_f32 v[208:209], v[12:13], v[160:161], v[208:209]
	v_pk_mul_f32 v[54:55], v[206:207], v[206:207]
	v_pk_mul_f32 v[56:57], v[206:207], v[174:175]
	v_pk_mul_f32 v[62:63], v[208:209], v[176:177]
	v_pk_fma_f32 v[54:55], v[208:209], v[208:209], v[54:55]
	v_cvt_pk_bf16_f32 v34, v206, v207
	v_cvt_pk_bf16_f32 v35, v208, v209
	v_cvt_pk_bf16_f32 v46, v56, v57
	v_cvt_pk_bf16_f32 v47, v62, v63
	v_add_f32_e32 v54, v54, v55
	v_add_f32_e32 v244, v244, v54
	v_pk_fma_f32 v[210:211], v[6:7], v[162:163], v[210:211]
	v_pk_fma_f32 v[212:213], v[8:9], v[164:165], v[212:213]
	v_pk_mul_f32 v[54:55], v[210:211], v[210:211]
	v_pk_mul_f32 v[56:57], v[210:211], v[178:179]
	v_pk_mul_f32 v[62:63], v[212:213], v[180:181]
	v_pk_fma_f32 v[54:55], v[212:213], v[212:213], v[54:55]
	v_cvt_pk_bf16_f32 v36, v210, v211
	v_cvt_pk_bf16_f32 v37, v212, v213
	v_cvt_pk_bf16_f32 v48, v56, v57
	v_cvt_pk_bf16_f32 v49, v62, v63
	v_add_f32_e32 v54, v54, v55
	v_add_f32_e32 v244, v244, v54
	v_permlane16_swap_b32_e32 v34, v36
	v_permlane16_swap_b32_e32 v35, v37
	v_permlane16_swap_b32_e32 v46, v48
	v_permlane16_swap_b32_e32 v47, v49
	global_store_dwordx4 v[246:247], v[34:37], off offset:256
	global_store_dwordx4 v[216:217], v[46:49], off offset:256
	v_mov_b32_e32 v54, v244
	v_mov_b32_e32 v55, v244
	s_nop 1
	v_permlane32_swap_b32_e32 v54, v55
	v_add_f32_e32 v244, v244, v55
	v_mov_b32_e32 v54, v244
	v_mov_b32_e32 v55, v244
	s_nop 1
	v_permlane16_swap_b32_e32 v54, v55
	v_add_f32_e32 v244, v244, v55
	s_mov_b64 exec, 0xffff
	global_store_dword v[248:249], v244, off
	s_mov_b64 exec, -1
